# MLA loop tiles: PV restructured k-step-outer, the exp/row-sum/bf16-convert of the next 16 keys issued between the PV MFMAs (f32 math unchanged)
# speedup vs baseline: 1.0051x; 1.0027x over previous
.LBB0_1431:
	v_exp_f32_e32 v114, v114
	v_exp_f32_e32 v115, v115
	v_exp_f32_e32 v116, v116
	v_exp_f32_e32 v117, v117
	v_exp_f32_e32 v118, v118
	v_exp_f32_e32 v119, v119
	v_exp_f32_e32 v120, v120
	v_exp_f32_e32 v121, v121
	ds_read_b64_tr_b16 v[238:239], v190 offset:0x4000
	ds_read_b64_tr_b16 v[240:241], v190 offset:0x4800
	ds_read_b64_tr_b16 v[242:243], v190 offset:0x4200
	ds_read_b64_tr_b16 v[244:245], v190 offset:0x4a00
	ds_read_b64_tr_b16 v[246:247], v190 offset:0x4400
	ds_read_b64_tr_b16 v[248:249], v190 offset:0x4c00
	ds_read_b64_tr_b16 v[250:251], v190 offset:0x4600
	ds_read_b64_tr_b16 v[252:253], v190 offset:0x4e00
	v_mov_b32_e32 v165, v163
	v_mov_b32_e32 v167, v163
	v_lshl_add_u64 v[168:169], v[168:169], 0, v[162:163]
	v_lshl_add_u64 v[170:171], v[170:171], 0, v[164:165]
	v_lshl_add_u64 v[172:173], v[172:173], 0, v[166:167]
	v_lshl_add_u64 v[180:181], v[174:175], 0, s[76:77]
	v_lshl_add_u64 v[178:179], v[176:177], 0, s[76:77]
	v_add_f32_e32 v232, v114, v115
	v_add_f32_e32 v233, v116, v117
	v_add_f32_e32 v232, v232, v233
	v_add_f32_e32 v233, v118, v119
	v_add_f32_e32 v234, v120, v121
	v_add_f32_e32 v233, v233, v234
	v_add_f32_e32 v213, v232, v233
	v_cvt_pk_bf16_f32 v114, v114, v115
	v_cvt_pk_bf16_f32 v115, v116, v117
	v_cvt_pk_bf16_f32 v116, v118, v119
	v_cvt_pk_bf16_f32 v117, v120, v121
	s_nop 1
	v_permlane32_swap_b32_e32 v114, v116
	v_permlane32_swap_b32_e32 v115, v117
	ds_read_b64_tr_b16 v[216:217], v190 offset:0x5000
	ds_read_b64_tr_b16 v[218:219], v190 offset:0x5800
	ds_read_b64_tr_b16 v[220:221], v190 offset:0x5200
	ds_read_b64_tr_b16 v[222:223], v190 offset:0x5a00
	ds_read_b64_tr_b16 v[224:225], v190 offset:0x5400
	ds_read_b64_tr_b16 v[226:227], v190 offset:0x5c00
	ds_read_b64_tr_b16 v[228:229], v190 offset:0x5600
	ds_read_b64_tr_b16 v[230:231], v190 offset:0x5e00
	s_waitcnt lgkmcnt(8)
	v_mfma_f32_32x32x16_bf16 v[18:33], v[114:117], v[238:241], v[18:33]
	v_exp_f32_e32 v122, v122
	v_exp_f32_e32 v123, v123
	v_exp_f32_e32 v124, v124
	v_mfma_f32_32x32x16_bf16 v[34:49], v[114:117], v[242:245], v[34:49]
	v_exp_f32_e32 v125, v125
	v_exp_f32_e32 v126, v126
	v_exp_f32_e32 v127, v127
	v_mfma_f32_32x32x16_bf16 v[50:65], v[114:117], v[246:249], v[50:65]
	v_exp_f32_e32 v128, v128
	v_exp_f32_e32 v129, v129
	v_add_f32_e32 v232, v122, v123
	v_add_f32_e32 v233, v124, v125
	v_mfma_f32_32x32x16_bf16 v[66:81], v[114:117], v[250:253], v[66:81]
	v_add_f32_e32 v232, v232, v233
	v_add_f32_e32 v233, v126, v127
	v_add_f32_e32 v234, v128, v129
	v_add_f32_e32 v233, v233, v234
	v_add_f32_e32 v232, v232, v233
	v_add_f32_e32 v213, v213, v232
	v_cvt_pk_bf16_f32 v122, v122, v123
	v_cvt_pk_bf16_f32 v123, v124, v125
	v_cvt_pk_bf16_f32 v124, v126, v127
	v_cvt_pk_bf16_f32 v125, v128, v129
	s_nop 1
	v_permlane32_swap_b32_e32 v122, v124
	v_permlane32_swap_b32_e32 v123, v125
	ds_read_b64_tr_b16 v[238:239], v190 offset:0x6000
	ds_read_b64_tr_b16 v[240:241], v190 offset:0x6800
	ds_read_b64_tr_b16 v[242:243], v190 offset:0x6200
	ds_read_b64_tr_b16 v[244:245], v190 offset:0x6a00
	ds_read_b64_tr_b16 v[246:247], v190 offset:0x6400
	ds_read_b64_tr_b16 v[248:249], v190 offset:0x6c00
	ds_read_b64_tr_b16 v[250:251], v190 offset:0x6600
	ds_read_b64_tr_b16 v[252:253], v190 offset:0x6e00
	s_waitcnt lgkmcnt(8)
	v_mfma_f32_32x32x16_bf16 v[18:33], v[122:125], v[216:219], v[18:33]
	v_exp_f32_e32 v98, v98
	v_exp_f32_e32 v99, v99
	v_exp_f32_e32 v100, v100
	v_mfma_f32_32x32x16_bf16 v[34:49], v[122:125], v[220:223], v[34:49]
	v_exp_f32_e32 v101, v101
	v_exp_f32_e32 v102, v102
	v_exp_f32_e32 v103, v103
	v_mfma_f32_32x32x16_bf16 v[50:65], v[122:125], v[224:227], v[50:65]
	v_exp_f32_e32 v104, v104
	v_exp_f32_e32 v105, v105
	v_add_f32_e32 v232, v98, v99
	v_add_f32_e32 v233, v100, v101
	v_mfma_f32_32x32x16_bf16 v[66:81], v[122:125], v[228:231], v[66:81]
	v_add_f32_e32 v232, v232, v233
	v_add_f32_e32 v233, v102, v103
	v_add_f32_e32 v234, v104, v105
	v_add_f32_e32 v233, v233, v234
	v_add_f32_e32 v232, v232, v233
	v_add_f32_e32 v213, v213, v232
	v_cvt_pk_bf16_f32 v98, v98, v99
	v_cvt_pk_bf16_f32 v99, v100, v101
	v_cvt_pk_bf16_f32 v100, v102, v103
	v_cvt_pk_bf16_f32 v101, v104, v105
	s_nop 1
	v_permlane32_swap_b32_e32 v98, v100
	v_permlane32_swap_b32_e32 v99, v101
	ds_read_b64_tr_b16 v[216:217], v190 offset:0x7000
	ds_read_b64_tr_b16 v[218:219], v190 offset:0x7800
	ds_read_b64_tr_b16 v[220:221], v190 offset:0x7200
	ds_read_b64_tr_b16 v[222:223], v190 offset:0x7a00
	ds_read_b64_tr_b16 v[224:225], v190 offset:0x7400
	ds_read_b64_tr_b16 v[226:227], v190 offset:0x7c00
	ds_read_b64_tr_b16 v[228:229], v190 offset:0x7600
	ds_read_b64_tr_b16 v[230:231], v190 offset:0x7e00
	s_waitcnt lgkmcnt(8)
	v_mfma_f32_32x32x16_bf16 v[18:33], v[98:101], v[238:241], v[18:33]
	v_exp_f32_e32 v106, v106
	v_exp_f32_e32 v107, v107
	v_exp_f32_e32 v108, v108
	v_mfma_f32_32x32x16_bf16 v[34:49], v[98:101], v[242:245], v[34:49]
	v_exp_f32_e32 v109, v109
	v_exp_f32_e32 v110, v110
	v_exp_f32_e32 v111, v111
	v_mfma_f32_32x32x16_bf16 v[50:65], v[98:101], v[246:249], v[50:65]
	v_exp_f32_e32 v112, v112
	v_exp_f32_e32 v113, v113
	v_add_f32_e32 v232, v106, v107
	v_add_f32_e32 v233, v108, v109
	v_mfma_f32_32x32x16_bf16 v[66:81], v[98:101], v[250:253], v[66:81]
	v_add_f32_e32 v232, v232, v233
	v_add_f32_e32 v233, v110, v111
	v_add_f32_e32 v234, v112, v113
	v_add_f32_e32 v233, v233, v234
	v_add_f32_e32 v232, v232, v233
	v_add_f32_e32 v213, v213, v232
	v_cvt_pk_bf16_f32 v106, v106, v107
	v_cvt_pk_bf16_f32 v107, v108, v109
	v_cvt_pk_bf16_f32 v108, v110, v111
	v_cvt_pk_bf16_f32 v109, v112, v113
	s_nop 1
	v_permlane32_swap_b32_e32 v106, v108
	v_permlane32_swap_b32_e32 v107, v109
	v_mov_b32_e32 v214, v213
	s_nop 1
	v_permlane32_swap_b32_e32 v213, v214
	s_waitcnt lgkmcnt(0)
	v_mfma_f32_32x32x16_bf16 v[18:33], v[106:109], v[216:219], v[18:33]
	s_waitcnt vmcnt(0)
	s_cmp_lt_u32 s11, s10
	s_cselect_b64 s[0:1], -1, 0
	s_cmp_ge_u32 s11, s10
	s_barrier
	ds_read_b128 v[232:235], v194 offset:32768
	ds_read_b128 v[216:219], v194 offset:45056
	ds_read_b128 v[238:241], v195 offset:32768
	ds_read_b128 v[242:245], v195 offset:45056
	ds_read_b128 v[246:249], v196 offset:32768
	ds_read_b128 v[250:253], v196 offset:45056
	v_mfma_f32_32x32x16_bf16 v[34:49], v[106:109], v[220:223], v[34:49]
	v_mfma_f32_32x32x16_bf16 v[50:65], v[106:109], v[224:227], v[50:65]
	v_mfma_f32_32x32x16_bf16 v[66:81], v[106:109], v[228:231], v[66:81]
	s_cbranch_scc1 .LBB0_1433
	s_add_i32 s13, s86, 0x4000
	s_mov_b32 s14, m0
	s_mov_b32 m0, s13
	s_nop 0
	global_load_lds_dwordx4 v[180:181], off
	s_mov_b32 m0, s14
	s_add_i32 s13, s3, 0x4000
	s_mov_b32 s14, m0
	s_mov_b32 m0, s13
	s_nop 0
	global_load_lds_dwordx4 v[178:179], off
	s_mov_b32 m0, s14
	v_lshl_add_u64 v[174:175], v[174:175], 0, s[30:31]
	v_lshl_add_u64 v[176:177], v[176:177], 0, s[30:31]
	s_branch .LBB0_1434

.LBB0_1440:
	v_exp_f32_e32 v114, v114
	v_exp_f32_e32 v115, v115
	v_exp_f32_e32 v116, v116
	v_exp_f32_e32 v117, v117
	v_exp_f32_e32 v118, v118
	v_exp_f32_e32 v119, v119
	v_exp_f32_e32 v120, v120
	v_exp_f32_e32 v121, v121
	ds_read_b64_tr_b16 v[238:239], v190
	ds_read_b64_tr_b16 v[240:241], v190 offset:0x800
	ds_read_b64_tr_b16 v[242:243], v190 offset:0x200
	ds_read_b64_tr_b16 v[244:245], v190 offset:0xa00
	ds_read_b64_tr_b16 v[246:247], v190 offset:0x400
	ds_read_b64_tr_b16 v[248:249], v190 offset:0xc00
	ds_read_b64_tr_b16 v[250:251], v190 offset:0x600
	ds_read_b64_tr_b16 v[252:253], v190 offset:0xe00
	v_add_f32_e32 v232, v114, v115
	v_add_f32_e32 v233, v116, v117
	v_add_f32_e32 v232, v232, v233
	v_add_f32_e32 v233, v118, v119
	v_add_f32_e32 v234, v120, v121
	v_add_f32_e32 v233, v233, v234
	v_add_f32_e32 v213, v232, v233
	v_cvt_pk_bf16_f32 v114, v114, v115
	v_cvt_pk_bf16_f32 v115, v116, v117
	v_cvt_pk_bf16_f32 v116, v118, v119
	v_cvt_pk_bf16_f32 v117, v120, v121
	s_nop 1
	v_permlane32_swap_b32_e32 v114, v116
	v_permlane32_swap_b32_e32 v115, v117
	ds_read_b64_tr_b16 v[216:217], v190 offset:0x1000
	ds_read_b64_tr_b16 v[218:219], v190 offset:0x1800
	ds_read_b64_tr_b16 v[220:221], v190 offset:0x1200
	ds_read_b64_tr_b16 v[222:223], v190 offset:0x1a00
	ds_read_b64_tr_b16 v[224:225], v190 offset:0x1400
	ds_read_b64_tr_b16 v[226:227], v190 offset:0x1c00
	ds_read_b64_tr_b16 v[228:229], v190 offset:0x1600
	ds_read_b64_tr_b16 v[230:231], v190 offset:0x1e00
	s_waitcnt lgkmcnt(8)
	v_mfma_f32_32x32x16_bf16 v[18:33], v[114:117], v[238:241], v[18:33]
	v_exp_f32_e32 v122, v122
	v_exp_f32_e32 v123, v123
	v_exp_f32_e32 v124, v124
	v_mfma_f32_32x32x16_bf16 v[34:49], v[114:117], v[242:245], v[34:49]
	v_exp_f32_e32 v125, v125
	v_exp_f32_e32 v126, v126
	v_exp_f32_e32 v127, v127
	v_mfma_f32_32x32x16_bf16 v[50:65], v[114:117], v[246:249], v[50:65]
	v_exp_f32_e32 v128, v128
	v_exp_f32_e32 v129, v129
	v_add_f32_e32 v232, v122, v123
	v_add_f32_e32 v233, v124, v125
	v_mfma_f32_32x32x16_bf16 v[66:81], v[114:117], v[250:253], v[66:81]
	v_add_f32_e32 v232, v232, v233
	v_add_f32_e32 v233, v126, v127
	v_add_f32_e32 v234, v128, v129
	v_add_f32_e32 v233, v233, v234
	v_add_f32_e32 v232, v232, v233
	v_add_f32_e32 v213, v213, v232
	v_cvt_pk_bf16_f32 v122, v122, v123
	v_cvt_pk_bf16_f32 v123, v124, v125
	v_cvt_pk_bf16_f32 v124, v126, v127
	v_cvt_pk_bf16_f32 v125, v128, v129
	s_nop 1
	v_permlane32_swap_b32_e32 v122, v124
	v_permlane32_swap_b32_e32 v123, v125
	ds_read_b64_tr_b16 v[238:239], v190 offset:0x2000
	ds_read_b64_tr_b16 v[240:241], v190 offset:0x2800
	ds_read_b64_tr_b16 v[242:243], v190 offset:0x2200
	ds_read_b64_tr_b16 v[244:245], v190 offset:0x2a00
	ds_read_b64_tr_b16 v[246:247], v190 offset:0x2400
	ds_read_b64_tr_b16 v[248:249], v190 offset:0x2c00
	ds_read_b64_tr_b16 v[250:251], v190 offset:0x2600
	ds_read_b64_tr_b16 v[252:253], v190 offset:0x2e00
	s_waitcnt lgkmcnt(8)
	v_mfma_f32_32x32x16_bf16 v[18:33], v[122:125], v[216:219], v[18:33]
	v_exp_f32_e32 v98, v98
	v_exp_f32_e32 v99, v99
	v_exp_f32_e32 v100, v100
	v_mfma_f32_32x32x16_bf16 v[34:49], v[122:125], v[220:223], v[34:49]
	v_exp_f32_e32 v101, v101
	v_exp_f32_e32 v102, v102
	v_exp_f32_e32 v103, v103
	v_mfma_f32_32x32x16_bf16 v[50:65], v[122:125], v[224:227], v[50:65]
	v_exp_f32_e32 v104, v104
	v_exp_f32_e32 v105, v105
	v_add_f32_e32 v232, v98, v99
	v_add_f32_e32 v233, v100, v101
	v_mfma_f32_32x32x16_bf16 v[66:81], v[122:125], v[228:231], v[66:81]
	v_add_f32_e32 v232, v232, v233
	v_add_f32_e32 v233, v102, v103
	v_add_f32_e32 v234, v104, v105
	v_add_f32_e32 v233, v233, v234
	v_add_f32_e32 v232, v232, v233
	v_add_f32_e32 v213, v213, v232
	v_cvt_pk_bf16_f32 v98, v98, v99
	v_cvt_pk_bf16_f32 v99, v100, v101
	v_cvt_pk_bf16_f32 v100, v102, v103
	v_cvt_pk_bf16_f32 v101, v104, v105
	s_nop 1
	v_permlane32_swap_b32_e32 v98, v100
	v_permlane32_swap_b32_e32 v99, v101
	ds_read_b64_tr_b16 v[216:217], v190 offset:0x3000
	ds_read_b64_tr_b16 v[218:219], v190 offset:0x3800
	ds_read_b64_tr_b16 v[220:221], v190 offset:0x3200
	ds_read_b64_tr_b16 v[222:223], v190 offset:0x3a00
	ds_read_b64_tr_b16 v[224:225], v190 offset:0x3400
	ds_read_b64_tr_b16 v[226:227], v190 offset:0x3c00
	ds_read_b64_tr_b16 v[228:229], v190 offset:0x3600
	ds_read_b64_tr_b16 v[230:231], v190 offset:0x3e00
	s_waitcnt lgkmcnt(8)
	v_mfma_f32_32x32x16_bf16 v[18:33], v[98:101], v[238:241], v[18:33]
	v_exp_f32_e32 v106, v106
	v_exp_f32_e32 v107, v107
	v_exp_f32_e32 v108, v108
	v_mfma_f32_32x32x16_bf16 v[34:49], v[98:101], v[242:245], v[34:49]
	v_exp_f32_e32 v109, v109
	v_exp_f32_e32 v110, v110
	v_exp_f32_e32 v111, v111
	v_mfma_f32_32x32x16_bf16 v[50:65], v[98:101], v[246:249], v[50:65]
	v_exp_f32_e32 v112, v112
	v_exp_f32_e32 v113, v113
	v_add_f32_e32 v232, v106, v107
	v_add_f32_e32 v233, v108, v109
	v_mfma_f32_32x32x16_bf16 v[66:81], v[98:101], v[250:253], v[66:81]
	v_add_f32_e32 v232, v232, v233
	v_add_f32_e32 v233, v110, v111
	v_add_f32_e32 v234, v112, v113
	v_add_f32_e32 v233, v233, v234
	v_add_f32_e32 v232, v232, v233
	v_add_f32_e32 v213, v213, v232
	v_cvt_pk_bf16_f32 v106, v106, v107
	v_cvt_pk_bf16_f32 v107, v108, v109
	v_cvt_pk_bf16_f32 v108, v110, v111
	v_cvt_pk_bf16_f32 v109, v112, v113
	s_nop 1
	v_permlane32_swap_b32_e32 v106, v108
	v_permlane32_swap_b32_e32 v107, v109
	v_mov_b32_e32 v214, v213
	s_nop 1
	v_permlane32_swap_b32_e32 v213, v214
	v_add_f32_e32 v213, v213, v214
	v_add_f32_e32 v199, v165, v213
	s_waitcnt lgkmcnt(0)
	v_mfma_f32_32x32x16_bf16 v[18:33], v[106:109], v[216:219], v[18:33]
	s_waitcnt vmcnt(0)
	s_addk_i32 s12, 0x80
	s_add_i32 s8, s11, 2
	s_add_i32 s9, s11, 1
	v_add_u32_e32 v212, 0xffffff80, v212
	s_cmp_lt_u32 s9, s10
	s_barrier
	ds_read_b128 v[178:181], v211
	ds_read_b128 v[214:217], v211 offset:12288
	ds_read_b128 v[238:241], v210
	ds_read_b128 v[242:245], v210 offset:12288
	ds_read_b128 v[246:249], v209
	ds_read_b128 v[250:253], v209 offset:12288
	v_mfma_f32_32x32x16_bf16 v[34:49], v[106:109], v[220:223], v[34:49]
	v_mfma_f32_32x32x16_bf16 v[50:65], v[106:109], v[224:227], v[50:65]
	v_mfma_f32_32x32x16_bf16 v[66:81], v[106:109], v[228:231], v[66:81]
	s_cbranch_scc0 .LBB0_1442
	s_mov_b32 s11, s8
	s_branch .LBB0_1425
